# non-FOLD EpiResid: four gate-vector loads issued together (counted vmcnt)
# baseline (speedup 1.0000x reference)
;     __device__ __forceinline__ void operator()(const f32x4 (&acc)[2][2][4][2], const Unit& u, int wr, int wc, int fr, int fq) const {
;         const int row0 = u.pm * BM + wr * 64 + fr, col0 = u.pn * BM + wc * 32 + 4 * fq;
;         const float* gp = gate + (size_t)(u.pm >> 4) * NMOD;
;         f32x4 gv[2][2], sv[2][2];
; #pragma unroll
;         for (int bj = 0; bj < 2; ++bj)
; #pragma unroll
;             for (int n = 0; n < 2; ++n) { gv[bj][n] = *(const f32x4*)(gp + col0 + bj * HALF + n * 16) * (HALFSC ? 0.5f : 1.0f);
;                 if (FOLD) sv[bj][n] = *(const f32x4*)(scn + (size_t)(u.pm >> 4) * NMOD + col0 + bj * HALF + n * 16) + 1.0f; }
; #pragma unroll
;         for (int ai = 0; ai < 2; ++ai)
; #pragma unroll
;             for (int m = 0; m < 4; ++m) { const int row = row0 + ai * HALF + m * 16; const size_t off = (size_t)row * D + col0;
;                 float ssq = 0.f;
; #pragma unroll
;                 for (int bj = 0; bj < 2; ++bj)
; #pragma unroll
;                     for (int n = 0; n < 2; ++n) { const f32x4 bs = *(const f32x4*)(base + off + bj * HALF + n * 16);
;                         const f32x4 o = bs + gv[bj][n] * acc[ai][bj][m][n];
;                         *(f32x4*)(out + off + bj * HALF + n * 16) = o;
.LBB0_1440:
	s_ashr_i32 s28, s55, 4
	v_lshl_or_b32 v144, s56, 8, v166
	s_mul_hi_i32 s29, s28, 0x9000
	s_mul_i32 s28, s28, 0x9000
	s_add_u32 s28, s43, s28
	v_ashrrev_i32_e32 v145, 31, v144
	s_addc_u32 s29, s44, s29
	v_lshlrev_b64 v[162:163], 2, v[144:145]
	v_lshl_add_u64 v[160:161], s[28:29], 0, v[162:163]
	global_load_dwordx4 v[176:179], v[160:161], off
	global_load_dwordx4 v[180:183], v[160:161], off offset:64
	global_load_dwordx4 v[184:187], v[160:161], off offset:512
	global_load_dwordx4 v[144:147], v[160:161], off offset:576
	v_lshl_add_u32 v174, s55, 8, v164
	v_ashrrev_i32_e32 v175, 31, v174
	v_readlane_b32 s56, v248, 0
	v_readlane_b32 s62, v248, 6
	v_readlane_b32 s63, v248, 7
	s_mov_b64 s[28:29], 0x80000
	v_readlane_b32 s57, v248, 1
	v_readlane_b32 s58, v248, 2
	v_readlane_b32 s59, v248, 3
	v_readlane_b32 s60, v248, 4
	v_readlane_b32 s61, v248, 5
	s_waitcnt vmcnt(3)
	v_pk_mul_f32 v[156:157], v[178:179], 0.5 op_sel_hi:[1,0]
	v_pk_mul_f32 v[158:159], v[176:177], 0.5 op_sel_hi:[1,0]
	s_waitcnt vmcnt(2)
	v_pk_mul_f32 v[152:153], v[182:183], 0.5 op_sel_hi:[1,0]
	v_pk_mul_f32 v[154:155], v[180:181], 0.5 op_sel_hi:[1,0]
	s_waitcnt vmcnt(1)
	v_pk_mul_f32 v[148:149], v[186:187], 0.5 op_sel_hi:[1,0]
	v_pk_mul_f32 v[150:151], v[184:185], 0.5 op_sel_hi:[1,0]
	v_lshlrev_b64 v[160:161], 12, v[174:175]
	v_lshl_add_u64 v[160:161], s[62:63], 0, v[160:161]
	v_lshl_add_u64 v[160:161], v[160:161], 0, v[162:163]
	global_load_dwordx4 v[216:219], v[160:161], off
	global_load_dwordx4 v[220:223], v[160:161], off offset:64
	global_load_dwordx4 v[236:239], v[160:161], off offset:512
	global_load_dwordx4 v[240:243], v[160:161], off offset:576
	s_waitcnt vmcnt(3)
	v_pk_mul_f32 v[146:147], v[146:147], 0.5 op_sel_hi:[1,0]
	v_pk_mul_f32 v[144:145], v[144:145], 0.5 op_sel_hi:[1,0]
	v_pk_fma_f32 v[126:127], v[126:127], v[156:157], v[218:219]
	v_pk_fma_f32 v[124:125], v[124:125], v[158:159], v[216:217]
	global_store_dwordx4 v[160:161], v[124:127], off
	s_waitcnt vmcnt(3)
	v_pk_fma_f32 v[122:123], v[122:123], v[152:153], v[222:223]
	v_pk_fma_f32 v[120:121], v[120:121], v[154:155], v[220:221]
	global_store_dwordx4 v[160:161], v[120:123], off offset:64
	s_waitcnt vmcnt(3)
	v_pk_fma_f32 v[118:119], v[118:119], v[148:149], v[238:239]
	v_pk_fma_f32 v[116:117], v[116:117], v[150:151], v[236:237]
	global_store_dwordx4 v[160:161], v[116:119], off offset:512
	s_waitcnt vmcnt(3)
	v_pk_fma_f32 v[114:115], v[114:115], v[146:147], v[242:243]
	v_pk_fma_f32 v[112:113], v[112:113], v[144:145], v[240:241]
	global_store_dwordx4 v[160:161], v[112:115], off offset:576
	s_nop 1
	v_or_b32_e32 v112, 16, v174
	v_ashrrev_i32_e32 v113, 31, v112
	v_lshlrev_b64 v[112:113], 12, v[112:113]
	v_lshl_add_u64 v[112:113], s[62:63], 0, v[112:113]
	v_lshl_add_u64 v[116:117], v[112:113], 0, v[162:163]
	global_load_dwordx4 v[216:219], v[116:117], off
	global_load_dwordx4 v[220:223], v[116:117], off offset:64
	global_load_dwordx4 v[236:239], v[116:117], off offset:512
	global_load_dwordx4 v[240:243], v[116:117], off offset:576
	s_waitcnt vmcnt(3)
	v_pk_fma_f32 v[110:111], v[110:111], v[156:157], v[218:219]
	v_pk_fma_f32 v[108:109], v[108:109], v[158:159], v[216:217]
	global_store_dwordx4 v[116:117], v[108:111], off
	s_waitcnt vmcnt(3)
	v_pk_fma_f32 v[106:107], v[106:107], v[152:153], v[222:223]
	v_pk_fma_f32 v[104:105], v[104:105], v[154:155], v[220:221]
	global_store_dwordx4 v[116:117], v[104:107], off offset:64
	s_waitcnt vmcnt(3)
	v_pk_fma_f32 v[102:103], v[102:103], v[148:149], v[238:239]
	v_pk_fma_f32 v[100:101], v[100:101], v[150:151], v[236:237]
	global_store_dwordx4 v[116:117], v[100:103], off offset:512
	s_waitcnt vmcnt(3)
	v_pk_fma_f32 v[98:99], v[98:99], v[146:147], v[242:243]
	v_pk_fma_f32 v[96:97], v[96:97], v[144:145], v[240:241]
	global_store_dwordx4 v[116:117], v[96:99], off offset:576
	s_nop 1
	v_or_b32_e32 v96, 32, v174
	v_ashrrev_i32_e32 v97, 31, v96
	v_lshlrev_b64 v[96:97], 12, v[96:97]
	v_lshl_add_u64 v[96:97], s[62:63], 0, v[96:97]
	v_lshl_add_u64 v[100:101], v[96:97], 0, v[162:163]
	global_load_dwordx4 v[216:219], v[100:101], off
	global_load_dwordx4 v[220:223], v[100:101], off offset:64
	global_load_dwordx4 v[236:239], v[100:101], off offset:512
	global_load_dwordx4 v[240:243], v[100:101], off offset:576
	s_waitcnt vmcnt(3)
	v_pk_fma_f32 v[94:95], v[94:95], v[156:157], v[218:219]
	v_pk_fma_f32 v[92:93], v[92:93], v[158:159], v[216:217]
	global_store_dwordx4 v[100:101], v[92:95], off
	s_waitcnt vmcnt(3)
	v_pk_fma_f32 v[90:91], v[90:91], v[152:153], v[222:223]
	v_pk_fma_f32 v[88:89], v[88:89], v[154:155], v[220:221]
	global_store_dwordx4 v[100:101], v[88:91], off offset:64
	s_waitcnt vmcnt(3)
	v_pk_fma_f32 v[86:87], v[86:87], v[148:149], v[238:239]
	v_pk_fma_f32 v[84:85], v[84:85], v[150:151], v[236:237]
	global_store_dwordx4 v[100:101], v[84:87], off offset:512
	s_waitcnt vmcnt(3)
	v_pk_fma_f32 v[82:83], v[82:83], v[146:147], v[242:243]
	v_pk_fma_f32 v[80:81], v[80:81], v[144:145], v[240:241]
	global_store_dwordx4 v[100:101], v[80:83], off offset:576
	s_nop 1
	v_or_b32_e32 v80, 48, v174
	v_ashrrev_i32_e32 v81, 31, v80
	v_lshlrev_b64 v[80:81], 12, v[80:81]
	v_lshl_add_u64 v[80:81], s[62:63], 0, v[80:81]
	v_lshl_add_u64 v[84:85], v[80:81], 0, v[162:163]
	global_load_dwordx4 v[216:219], v[84:85], off
	global_load_dwordx4 v[220:223], v[84:85], off offset:64
	global_load_dwordx4 v[236:239], v[84:85], off offset:512
	global_load_dwordx4 v[240:243], v[84:85], off offset:576
	s_waitcnt vmcnt(3)
;     __device__ __forceinline__ void operator()(const f32x4 (&acc)[2][2][4][2], const Unit& u, int wr, int wc, int fr, int fq) const {
;     ...
;         for (int ai = 0; ai < 2; ++ai)
; #pragma unroll
;             for (int m = 0; m < 4; ++m) { const int row = row0 + ai * HALF + m * 16; const size_t off = (size_t)row * D + col0;
;                 float ssq = 0.f;
; #pragma unroll
;                 for (int bj = 0; bj < 2; ++bj)
; #pragma unroll
;                     for (int n = 0; n < 2; ++n) { const f32x4 bs = *(const f32x4*)(base + off + bj * HALF + n * 16);
;                         const f32x4 o = bs + gv[bj][n] * acc[ai][bj][m][n];
;                         *(f32x4*)(out + off + bj * HALF + n * 16) = o;
	v_pk_fma_f32 v[78:79], v[78:79], v[156:157], v[218:219]
	v_pk_fma_f32 v[76:77], v[76:77], v[158:159], v[216:217]
	global_store_dwordx4 v[84:85], v[76:79], off
	s_waitcnt vmcnt(3)
	v_pk_fma_f32 v[74:75], v[74:75], v[152:153], v[222:223]
	v_pk_fma_f32 v[72:73], v[72:73], v[154:155], v[220:221]
	global_store_dwordx4 v[84:85], v[72:75], off offset:64
	s_waitcnt vmcnt(3)
	v_pk_fma_f32 v[70:71], v[70:71], v[148:149], v[238:239]
	v_pk_fma_f32 v[68:69], v[68:69], v[150:151], v[236:237]
	global_store_dwordx4 v[84:85], v[68:71], off offset:512
	s_waitcnt vmcnt(3)
	v_pk_fma_f32 v[64:65], v[64:65], v[144:145], v[240:241]
	v_lshl_add_u64 v[68:69], v[160:161], 0, s[28:29]
	s_mov_b32 s28, 0x80000
	v_pk_fma_f32 v[66:67], v[66:67], v[146:147], v[242:243]
	v_add_co_u32_e32 v70, vcc, s28, v160
	global_store_dwordx4 v[84:85], v[64:67], off offset:576
	s_nop 0
	v_addc_co_u32_e32 v71, vcc, 0, v161, vcc
	global_load_dwordx4 v[216:219], v[70:71], off
	global_load_dwordx4 v[220:223], v[68:69], off offset:64
	global_load_dwordx4 v[236:239], v[68:69], off offset:512
	global_load_dwordx4 v[240:243], v[68:69], off offset:576
	s_mov_b64 s[28:29], 0x90000
	s_waitcnt vmcnt(3)
	v_pk_fma_f32 v[62:63], v[62:63], v[156:157], v[218:219]
	v_pk_fma_f32 v[60:61], v[60:61], v[158:159], v[216:217]
	global_store_dwordx4 v[70:71], v[60:63], off
	s_waitcnt vmcnt(3)
	v_pk_fma_f32 v[58:59], v[58:59], v[152:153], v[222:223]
	v_pk_fma_f32 v[56:57], v[56:57], v[154:155], v[220:221]
	global_store_dwordx4 v[68:69], v[56:59], off offset:64
	s_waitcnt vmcnt(3)
	v_pk_fma_f32 v[54:55], v[54:55], v[148:149], v[238:239]
	v_pk_fma_f32 v[52:53], v[52:53], v[150:151], v[236:237]
	global_store_dwordx4 v[68:69], v[52:55], off offset:512
	s_waitcnt vmcnt(3)
	v_pk_fma_f32 v[50:51], v[50:51], v[146:147], v[242:243]
	v_pk_fma_f32 v[48:49], v[48:49], v[144:145], v[240:241]
	global_store_dwordx4 v[68:69], v[48:51], off offset:576
	s_nop 1
	v_lshl_add_u64 v[48:49], v[160:161], 0, s[28:29]
	s_mov_b32 s28, 0x90000
	v_add_co_u32_e32 v54, vcc, s28, v160
	s_mov_b64 s[28:29], 0xa0000
	s_nop 0
	v_addc_co_u32_e32 v55, vcc, 0, v161, vcc
	global_load_dwordx4 v[216:219], v[54:55], off
	global_load_dwordx4 v[220:223], v[48:49], off offset:64
	global_load_dwordx4 v[236:239], v[48:49], off offset:512
	global_load_dwordx4 v[240:243], v[48:49], off offset:576
	s_waitcnt vmcnt(3)
	v_pk_fma_f32 v[46:47], v[46:47], v[156:157], v[218:219]
	v_pk_fma_f32 v[44:45], v[44:45], v[158:159], v[216:217]
	global_store_dwordx4 v[54:55], v[44:47], off
	s_waitcnt vmcnt(3)
	v_pk_fma_f32 v[42:43], v[42:43], v[152:153], v[222:223]
	v_pk_fma_f32 v[40:41], v[40:41], v[154:155], v[220:221]
	global_store_dwordx4 v[48:49], v[40:43], off offset:64
	s_waitcnt vmcnt(3)
	v_pk_fma_f32 v[38:39], v[38:39], v[148:149], v[238:239]
	v_pk_fma_f32 v[36:37], v[36:37], v[150:151], v[236:237]
	global_store_dwordx4 v[48:49], v[36:39], off offset:512
	s_waitcnt vmcnt(3)
	v_pk_fma_f32 v[32:33], v[32:33], v[144:145], v[240:241]
	v_lshl_add_u64 v[36:37], v[160:161], 0, s[28:29]
	s_mov_b32 s28, 0xa0000
	v_pk_fma_f32 v[34:35], v[34:35], v[146:147], v[242:243]
	v_add_co_u32_e32 v38, vcc, s28, v160
	global_store_dwordx4 v[48:49], v[32:35], off offset:576
	s_nop 0
	v_addc_co_u32_e32 v39, vcc, 0, v161, vcc
	global_load_dwordx4 v[216:219], v[38:39], off
	global_load_dwordx4 v[220:223], v[36:37], off offset:64
	global_load_dwordx4 v[236:239], v[36:37], off offset:512
	global_load_dwordx4 v[240:243], v[36:37], off offset:576
	s_mov_b64 s[28:29], 0xb0000
	s_waitcnt vmcnt(3)
	v_pk_fma_f32 v[30:31], v[30:31], v[156:157], v[218:219]
	v_pk_fma_f32 v[28:29], v[28:29], v[158:159], v[216:217]
	global_store_dwordx4 v[38:39], v[28:31], off
	s_waitcnt vmcnt(3)
	v_pk_fma_f32 v[26:27], v[26:27], v[152:153], v[222:223]
	v_pk_fma_f32 v[24:25], v[24:25], v[154:155], v[220:221]
	global_store_dwordx4 v[36:37], v[24:27], off offset:64
	s_waitcnt vmcnt(3)
	v_pk_fma_f32 v[22:23], v[22:23], v[148:149], v[238:239]
	v_pk_fma_f32 v[20:21], v[20:21], v[150:151], v[236:237]
	global_store_dwordx4 v[36:37], v[20:23], off offset:512
	s_waitcnt vmcnt(3)
	v_pk_fma_f32 v[18:19], v[18:19], v[146:147], v[242:243]
	v_pk_fma_f32 v[16:17], v[16:17], v[144:145], v[240:241]
	global_store_dwordx4 v[36:37], v[16:19], off offset:576
	s_nop 1
	v_lshl_add_u64 v[16:17], v[160:161], 0, s[28:29]
	s_mov_b32 s28, 0xb0000
	v_add_co_u32_e32 v22, vcc, s28, v160
	s_mov_b64 s[28:29], -1
	s_nop 0
	v_addc_co_u32_e32 v23, vcc, 0, v161, vcc
	global_load_dwordx4 v[216:219], v[22:23], off
	global_load_dwordx4 v[220:223], v[16:17], off offset:64
	global_load_dwordx4 v[236:239], v[16:17], off offset:512
	global_load_dwordx4 v[240:243], v[16:17], off offset:576
	s_and_b64 vcc, exec, s[0:1]
	s_waitcnt vmcnt(3)
	v_pk_fma_f32 v[14:15], v[14:15], v[156:157], v[218:219]
	v_pk_fma_f32 v[12:13], v[12:13], v[158:159], v[216:217]
	global_store_dwordx4 v[22:23], v[12:15], off
	s_waitcnt vmcnt(3)
	v_pk_fma_f32 v[10:11], v[10:11], v[152:153], v[222:223]
	v_pk_fma_f32 v[8:9], v[8:9], v[154:155], v[220:221]
	global_store_dwordx4 v[16:17], v[8:11], off offset:64
	s_waitcnt vmcnt(3)
	v_pk_fma_f32 v[6:7], v[6:7], v[148:149], v[238:239]
	v_pk_fma_f32 v[4:5], v[4:5], v[150:151], v[236:237]
	global_store_dwordx4 v[16:17], v[4:7], off offset:512
	s_waitcnt vmcnt(3)
	v_pk_fma_f32 v[2:3], v[2:3], v[146:147], v[242:243]
	v_pk_fma_f32 v[0:1], v[0:1], v[144:145], v[240:241]
	global_store_dwordx4 v[16:17], v[0:3], off offset:576
	s_cbranch_vccnz .LBB0_1424
	s_andn2_b64 vcc, exec, s[14:15]
	s_cbranch_vccnz .LBB0_1423
	s_barrier
	s_branch .LBB0_1423

;     __device__ __forceinline__ void operator()(const f32x4 (&acc)[2][2][4][2], const Unit& u, int wr, int wc, int fr, int fq) const {
;         const int row0 = u.pm * BM + wr * 64 + fr, col0 = u.pn * BM + wc * 32 + 4 * fq;
;         const float* gp = gate + (size_t)(u.pm >> 4) * NMOD;
;         f32x4 gv[2][2], sv[2][2];
; #pragma unroll
;         for (int bj = 0; bj < 2; ++bj)
; #pragma unroll
;             for (int n = 0; n < 2; ++n) { gv[bj][n] = *(const f32x4*)(gp + col0 + bj * HALF + n * 16) * (HALFSC ? 0.5f : 1.0f);
;                 if (FOLD) sv[bj][n] = *(const f32x4*)(scn + (size_t)(u.pm >> 4) * NMOD + col0 + bj * HALF + n * 16) + 1.0f; }
; #pragma unroll
;         for (int ai = 0; ai < 2; ++ai)
; #pragma unroll
;             for (int m = 0; m < 4; ++m) { const int row = row0 + ai * HALF + m * 16; const size_t off = (size_t)row * D + col0;
;                 float ssq = 0.f;
; #pragma unroll
;                 for (int bj = 0; bj < 2; ++bj)
; #pragma unroll
;                     for (int n = 0; n < 2; ++n) { const f32x4 bs = *(const f32x4*)(base + off + bj * HALF + n * 16);
;                         const f32x4 o = bs + gv[bj][n] * acc[ai][bj][m][n];
;                         *(f32x4*)(out + off + bj * HALF + n * 16) = o;
.LBB0_2613:
	s_ashr_i32 s22, s46, 4
	v_lshl_or_b32 v144, s47, 8, v166
	s_mul_hi_i32 s23, s22, 0x9000
	s_mul_i32 s22, s22, 0x9000
	s_add_u32 s22, s36, s22
	v_ashrrev_i32_e32 v145, 31, v144
	s_addc_u32 s23, s37, s23
	v_lshlrev_b64 v[162:163], 2, v[144:145]
	v_lshl_add_u64 v[160:161], s[22:23], 0, v[162:163]
	global_load_dwordx4 v[176:179], v[160:161], off
	global_load_dwordx4 v[180:183], v[160:161], off offset:64
	global_load_dwordx4 v[184:187], v[160:161], off offset:512
	global_load_dwordx4 v[144:147], v[160:161], off offset:576
	v_lshl_add_u32 v174, s46, 8, v164
	v_readlane_b32 s48, v248, 0
	v_ashrrev_i32_e32 v175, 31, v174
	v_readlane_b32 s54, v248, 6
	v_readlane_b32 s55, v248, 7
	s_mov_b64 s[22:23], s[54:55]
	v_readlane_b32 s49, v248, 1
	v_readlane_b32 s50, v248, 2
	v_readlane_b32 s51, v248, 3
	v_readlane_b32 s52, v248, 4
	v_readlane_b32 s53, v248, 5
	s_waitcnt vmcnt(3)
	v_pk_mul_f32 v[156:157], v[178:179], 0.5 op_sel_hi:[1,0]
	v_pk_mul_f32 v[158:159], v[176:177], 0.5 op_sel_hi:[1,0]
	s_waitcnt vmcnt(2)
	v_pk_mul_f32 v[152:153], v[182:183], 0.5 op_sel_hi:[1,0]
	v_pk_mul_f32 v[154:155], v[180:181], 0.5 op_sel_hi:[1,0]
	s_waitcnt vmcnt(1)
	v_pk_mul_f32 v[148:149], v[186:187], 0.5 op_sel_hi:[1,0]
	v_pk_mul_f32 v[150:151], v[184:185], 0.5 op_sel_hi:[1,0]
	v_lshlrev_b64 v[160:161], 12, v[174:175]
	v_lshl_add_u64 v[160:161], s[22:23], 0, v[160:161]
	v_lshl_add_u64 v[160:161], v[160:161], 0, v[162:163]
	global_load_dwordx4 v[216:219], v[160:161], off
	global_load_dwordx4 v[220:223], v[160:161], off offset:64
	global_load_dwordx4 v[236:239], v[160:161], off offset:512
	global_load_dwordx4 v[240:243], v[160:161], off offset:576
	s_waitcnt vmcnt(3)
	v_pk_mul_f32 v[146:147], v[146:147], 0.5 op_sel_hi:[1,0]
	v_pk_mul_f32 v[144:145], v[144:145], 0.5 op_sel_hi:[1,0]
	v_pk_fma_f32 v[126:127], v[126:127], v[156:157], v[218:219]
	v_pk_fma_f32 v[124:125], v[124:125], v[158:159], v[216:217]
	global_store_dwordx4 v[160:161], v[124:127], off
	s_waitcnt vmcnt(3)
	v_pk_fma_f32 v[122:123], v[122:123], v[152:153], v[222:223]
	v_pk_fma_f32 v[120:121], v[120:121], v[154:155], v[220:221]
	global_store_dwordx4 v[160:161], v[120:123], off offset:64
	s_waitcnt vmcnt(3)
	v_pk_fma_f32 v[118:119], v[118:119], v[148:149], v[238:239]
	v_pk_fma_f32 v[116:117], v[116:117], v[150:151], v[236:237]
	global_store_dwordx4 v[160:161], v[116:119], off offset:512
	s_waitcnt vmcnt(3)
	v_pk_fma_f32 v[114:115], v[114:115], v[146:147], v[242:243]
	v_pk_fma_f32 v[112:113], v[112:113], v[144:145], v[240:241]
	global_store_dwordx4 v[160:161], v[112:115], off offset:576
	s_nop 1
	v_or_b32_e32 v112, 16, v174
	v_ashrrev_i32_e32 v113, 31, v112
	v_lshlrev_b64 v[112:113], 12, v[112:113]
	v_lshl_add_u64 v[112:113], s[22:23], 0, v[112:113]
	v_lshl_add_u64 v[116:117], v[112:113], 0, v[162:163]
	global_load_dwordx4 v[216:219], v[116:117], off
	global_load_dwordx4 v[220:223], v[116:117], off offset:64
	global_load_dwordx4 v[236:239], v[116:117], off offset:512
	global_load_dwordx4 v[240:243], v[116:117], off offset:576
	s_waitcnt vmcnt(3)
	v_pk_fma_f32 v[110:111], v[110:111], v[156:157], v[218:219]
	v_pk_fma_f32 v[108:109], v[108:109], v[158:159], v[216:217]
	global_store_dwordx4 v[116:117], v[108:111], off
	s_waitcnt vmcnt(3)
	v_pk_fma_f32 v[106:107], v[106:107], v[152:153], v[222:223]
	v_pk_fma_f32 v[104:105], v[104:105], v[154:155], v[220:221]
	global_store_dwordx4 v[116:117], v[104:107], off offset:64
	s_waitcnt vmcnt(3)
	v_pk_fma_f32 v[102:103], v[102:103], v[148:149], v[238:239]
	v_pk_fma_f32 v[100:101], v[100:101], v[150:151], v[236:237]
	global_store_dwordx4 v[116:117], v[100:103], off offset:512
	s_waitcnt vmcnt(3)
	v_pk_fma_f32 v[98:99], v[98:99], v[146:147], v[242:243]
	v_pk_fma_f32 v[96:97], v[96:97], v[144:145], v[240:241]
	global_store_dwordx4 v[116:117], v[96:99], off offset:576
	s_nop 1
	v_or_b32_e32 v96, 32, v174
	v_ashrrev_i32_e32 v97, 31, v96
	v_lshlrev_b64 v[96:97], 12, v[96:97]
	v_lshl_add_u64 v[96:97], s[22:23], 0, v[96:97]
	v_lshl_add_u64 v[100:101], v[96:97], 0, v[162:163]
	global_load_dwordx4 v[216:219], v[100:101], off
	global_load_dwordx4 v[220:223], v[100:101], off offset:64
	global_load_dwordx4 v[236:239], v[100:101], off offset:512
	global_load_dwordx4 v[240:243], v[100:101], off offset:576
	s_waitcnt vmcnt(3)
	v_pk_fma_f32 v[94:95], v[94:95], v[156:157], v[218:219]
	v_pk_fma_f32 v[92:93], v[92:93], v[158:159], v[216:217]
	global_store_dwordx4 v[100:101], v[92:95], off
	s_waitcnt vmcnt(3)
	v_pk_fma_f32 v[90:91], v[90:91], v[152:153], v[222:223]
	v_pk_fma_f32 v[88:89], v[88:89], v[154:155], v[220:221]
	global_store_dwordx4 v[100:101], v[88:91], off offset:64
	s_waitcnt vmcnt(3)
	v_pk_fma_f32 v[86:87], v[86:87], v[148:149], v[238:239]
	v_pk_fma_f32 v[84:85], v[84:85], v[150:151], v[236:237]
	global_store_dwordx4 v[100:101], v[84:87], off offset:512
	s_waitcnt vmcnt(3)
	v_pk_fma_f32 v[82:83], v[82:83], v[146:147], v[242:243]
	v_pk_fma_f32 v[80:81], v[80:81], v[144:145], v[240:241]
	global_store_dwordx4 v[100:101], v[80:83], off offset:576
	s_nop 1
	v_or_b32_e32 v80, 48, v174
	v_ashrrev_i32_e32 v81, 31, v80
	v_lshlrev_b64 v[80:81], 12, v[80:81]
	v_lshl_add_u64 v[80:81], s[22:23], 0, v[80:81]
	v_lshl_add_u64 v[84:85], v[80:81], 0, v[162:163]
	global_load_dwordx4 v[216:219], v[84:85], off
	global_load_dwordx4 v[220:223], v[84:85], off offset:64
	global_load_dwordx4 v[236:239], v[84:85], off offset:512
	global_load_dwordx4 v[240:243], v[84:85], off offset:576
	s_mov_b64 s[22:23], 0x80000
	s_waitcnt vmcnt(3)
;     __device__ __forceinline__ void operator()(const f32x4 (&acc)[2][2][4][2], const Unit& u, int wr, int wc, int fr, int fq) const {
;     ...
;         for (int ai = 0; ai < 2; ++ai)
; #pragma unroll
;             for (int m = 0; m < 4; ++m) { const int row = row0 + ai * HALF + m * 16; const size_t off = (size_t)row * D + col0;
;                 float ssq = 0.f;
; #pragma unroll
;                 for (int bj = 0; bj < 2; ++bj)
; #pragma unroll
;                     for (int n = 0; n < 2; ++n) { const f32x4 bs = *(const f32x4*)(base + off + bj * HALF + n * 16);
;                         const f32x4 o = bs + gv[bj][n] * acc[ai][bj][m][n];
;                         *(f32x4*)(out + off + bj * HALF + n * 16) = o;
	v_pk_fma_f32 v[78:79], v[78:79], v[156:157], v[218:219]
	v_pk_fma_f32 v[76:77], v[76:77], v[158:159], v[216:217]
	global_store_dwordx4 v[84:85], v[76:79], off
	s_waitcnt vmcnt(3)
	v_pk_fma_f32 v[74:75], v[74:75], v[152:153], v[222:223]
	v_pk_fma_f32 v[72:73], v[72:73], v[154:155], v[220:221]
	global_store_dwordx4 v[84:85], v[72:75], off offset:64
	s_waitcnt vmcnt(3)
	v_pk_fma_f32 v[70:71], v[70:71], v[148:149], v[238:239]
	v_pk_fma_f32 v[68:69], v[68:69], v[150:151], v[236:237]
	global_store_dwordx4 v[84:85], v[68:71], off offset:512
	s_waitcnt vmcnt(3)
	v_pk_fma_f32 v[64:65], v[64:65], v[144:145], v[240:241]
	v_lshl_add_u64 v[68:69], v[160:161], 0, s[22:23]
	s_mov_b32 s22, 0x80000
	v_pk_fma_f32 v[66:67], v[66:67], v[146:147], v[242:243]
	v_add_co_u32_e32 v70, vcc, s22, v160
	global_store_dwordx4 v[84:85], v[64:67], off offset:576
	s_nop 0
	v_addc_co_u32_e32 v71, vcc, 0, v161, vcc
	global_load_dwordx4 v[216:219], v[70:71], off
	global_load_dwordx4 v[220:223], v[68:69], off offset:64
	global_load_dwordx4 v[236:239], v[68:69], off offset:512
	global_load_dwordx4 v[240:243], v[68:69], off offset:576
	s_mov_b64 s[22:23], 0x90000
	s_waitcnt vmcnt(3)
	v_pk_fma_f32 v[62:63], v[62:63], v[156:157], v[218:219]
	v_pk_fma_f32 v[60:61], v[60:61], v[158:159], v[216:217]
	global_store_dwordx4 v[70:71], v[60:63], off
	s_waitcnt vmcnt(3)
	v_pk_fma_f32 v[58:59], v[58:59], v[152:153], v[222:223]
	v_pk_fma_f32 v[56:57], v[56:57], v[154:155], v[220:221]
	global_store_dwordx4 v[68:69], v[56:59], off offset:64
	s_waitcnt vmcnt(3)
	v_pk_fma_f32 v[54:55], v[54:55], v[148:149], v[238:239]
	v_pk_fma_f32 v[52:53], v[52:53], v[150:151], v[236:237]
	global_store_dwordx4 v[68:69], v[52:55], off offset:512
	s_waitcnt vmcnt(3)
	v_pk_fma_f32 v[50:51], v[50:51], v[146:147], v[242:243]
	v_pk_fma_f32 v[48:49], v[48:49], v[144:145], v[240:241]
	global_store_dwordx4 v[68:69], v[48:51], off offset:576
	s_nop 1
	v_lshl_add_u64 v[48:49], v[160:161], 0, s[22:23]
	s_mov_b32 s22, 0x90000
	v_add_co_u32_e32 v54, vcc, s22, v160
	s_mov_b64 s[22:23], 0xa0000
	s_nop 0
	v_addc_co_u32_e32 v55, vcc, 0, v161, vcc
	global_load_dwordx4 v[216:219], v[54:55], off
	global_load_dwordx4 v[220:223], v[48:49], off offset:64
	global_load_dwordx4 v[236:239], v[48:49], off offset:512
	global_load_dwordx4 v[240:243], v[48:49], off offset:576
	s_waitcnt vmcnt(3)
	v_pk_fma_f32 v[46:47], v[46:47], v[156:157], v[218:219]
	v_pk_fma_f32 v[44:45], v[44:45], v[158:159], v[216:217]
	global_store_dwordx4 v[54:55], v[44:47], off
	s_waitcnt vmcnt(3)
	v_pk_fma_f32 v[42:43], v[42:43], v[152:153], v[222:223]
	v_pk_fma_f32 v[40:41], v[40:41], v[154:155], v[220:221]
	global_store_dwordx4 v[48:49], v[40:43], off offset:64
	s_waitcnt vmcnt(3)
	v_pk_fma_f32 v[38:39], v[38:39], v[148:149], v[238:239]
	v_pk_fma_f32 v[36:37], v[36:37], v[150:151], v[236:237]
	global_store_dwordx4 v[48:49], v[36:39], off offset:512
	s_waitcnt vmcnt(3)
	v_pk_fma_f32 v[32:33], v[32:33], v[144:145], v[240:241]
	v_lshl_add_u64 v[36:37], v[160:161], 0, s[22:23]
	s_mov_b32 s22, 0xa0000
	v_pk_fma_f32 v[34:35], v[34:35], v[146:147], v[242:243]
	v_add_co_u32_e32 v38, vcc, s22, v160
	global_store_dwordx4 v[48:49], v[32:35], off offset:576
	s_nop 0
	v_addc_co_u32_e32 v39, vcc, 0, v161, vcc
	global_load_dwordx4 v[216:219], v[38:39], off
	global_load_dwordx4 v[220:223], v[36:37], off offset:64
	global_load_dwordx4 v[236:239], v[36:37], off offset:512
	global_load_dwordx4 v[240:243], v[36:37], off offset:576
	s_mov_b64 s[22:23], 0xb0000
	s_waitcnt vmcnt(3)
	v_pk_fma_f32 v[30:31], v[30:31], v[156:157], v[218:219]
	v_pk_fma_f32 v[28:29], v[28:29], v[158:159], v[216:217]
	global_store_dwordx4 v[38:39], v[28:31], off
	s_waitcnt vmcnt(3)
	v_pk_fma_f32 v[26:27], v[26:27], v[152:153], v[222:223]
	v_pk_fma_f32 v[24:25], v[24:25], v[154:155], v[220:221]
	global_store_dwordx4 v[36:37], v[24:27], off offset:64
	s_waitcnt vmcnt(3)
	v_pk_fma_f32 v[22:23], v[22:23], v[148:149], v[238:239]
	v_pk_fma_f32 v[20:21], v[20:21], v[150:151], v[236:237]
	global_store_dwordx4 v[36:37], v[20:23], off offset:512
	s_waitcnt vmcnt(3)
	v_pk_fma_f32 v[18:19], v[18:19], v[146:147], v[242:243]
	v_pk_fma_f32 v[16:17], v[16:17], v[144:145], v[240:241]
	global_store_dwordx4 v[36:37], v[16:19], off offset:576
	s_nop 1
	v_lshl_add_u64 v[16:17], v[160:161], 0, s[22:23]
	s_mov_b32 s22, 0xb0000
	v_add_co_u32_e32 v22, vcc, s22, v160
	s_mov_b64 s[22:23], -1
	s_nop 0
	v_addc_co_u32_e32 v23, vcc, 0, v161, vcc
	global_load_dwordx4 v[216:219], v[22:23], off
	global_load_dwordx4 v[220:223], v[16:17], off offset:64
	global_load_dwordx4 v[236:239], v[16:17], off offset:512
	global_load_dwordx4 v[240:243], v[16:17], off offset:576
	s_and_b64 vcc, exec, s[0:1]
	s_waitcnt vmcnt(3)
	v_pk_fma_f32 v[14:15], v[14:15], v[156:157], v[218:219]
	v_pk_fma_f32 v[12:13], v[12:13], v[158:159], v[216:217]
	global_store_dwordx4 v[22:23], v[12:15], off
	s_waitcnt vmcnt(3)
	v_pk_fma_f32 v[10:11], v[10:11], v[152:153], v[222:223]
	v_pk_fma_f32 v[8:9], v[8:9], v[154:155], v[220:221]
	global_store_dwordx4 v[16:17], v[8:11], off offset:64
	s_waitcnt vmcnt(3)
	v_pk_fma_f32 v[6:7], v[6:7], v[148:149], v[238:239]
	v_pk_fma_f32 v[4:5], v[4:5], v[150:151], v[236:237]
	global_store_dwordx4 v[16:17], v[4:7], off offset:512
	s_waitcnt vmcnt(3)
	v_pk_fma_f32 v[2:3], v[2:3], v[146:147], v[242:243]
	v_pk_fma_f32 v[0:1], v[0:1], v[144:145], v[240:241]
	global_store_dwordx4 v[16:17], v[0:3], off offset:576
	s_cbranch_vccnz .LBB0_2597
	s_andn2_b64 vcc, exec, s[10:11]
	s_cbranch_vccnz .LBB0_2596
	s_barrier
	s_branch .LBB0_2596
